# v098 + second P10 workgroup barrier per token, placed after the first v-sweep's prologue loads are issued
# baseline (speedup 1.0000x reference)
; __device__ __forceinline__ float gelu1(float x) { return 0.5f * x * (1.0f + erff(x * 0.70710678118654752f)); }
; #define PV_LOAD(BUF, EV, S0) do { _Pragma("unroll") for (int i = 0; i < 8; ++i) { const int row_ = __builtin_amdgcn_readlane(EV, (S0) + i); BUF[i & 3][i >> 2] = *(const u32x4*)(PV8 + (size_t)row_ * 1024 + lane * 16); } } while (0)
; __global__ void __launch_bounds__(NT, 2) mk_fwd(Args args) {
;     ...
;                 const float d = dv * SCL[ev];
;                 const float a = gelu1(d) * gv * SCL[16384 + ev];
;                 if (hh) act1 = a; else act0 = a;
;             }
;     ...
;             f32x2 acc2[16];
; #pragma unroll
;             for (int i = 0; i < 16; ++i) acc2[i] = (f32x2){0.f, 0.f};
;     ...
; #pragma unroll
;             for (int hh = 0; hh < 2; ++hh) {
;                 const int ev = hh ? e1 : e0; const float av = hh ? act1 : act0;
;                 PV_LOAD(bA, ev, 0);
; #pragma unroll 1
;                 for (int s = 0; s < 64; s += 16) {
;                     PV_LOAD(bB, ev, s + 8);
;                     PV_ACC(bA, av, s);
;                     if (s + 16 < 64) PV_LOAD(bA, ev, s + 16);
;                     PV_ACC(bB, av, s + 8);
.LBB0_902:
	s_andn2_saveexec_b64 s[4:5], s[4:5]
	v_mul_f32_e32 v2, v109, v109
	v_fmamk_f32 v3, v2, 0xba1345e1, v152
	v_fmaak_f32 v3, v2, v3, 0xbcdac9b8
	v_fmaak_f32 v3, v2, v3, 0x3de703be
	v_fmaak_f32 v3, v2, v3, 0xbec09330
	v_fmaak_f32 v2, v2, v3, 0x3e0375d0
	v_fma_f32 v157, |v109|, v2, |v109|
	s_or_b64 exec, exec, s[4:5]
	v_readlane_b32 s4, v108, 0
	s_ashr_i32 s5, s4, 31
	s_lshl_b64 s[4:5], s[4:5], 10
	v_lshl_add_u64 v[2:3], v[100:101], 0, s[4:5]
	v_readlane_b32 s4, v108, 1
	s_ashr_i32 s5, s4, 31
	s_lshl_b64 s[4:5], s[4:5], 10
	v_lshl_add_u64 v[4:5], v[100:101], 0, s[4:5]
	v_readlane_b32 s4, v108, 2
	s_ashr_i32 s5, s4, 31
	s_lshl_b64 s[4:5], s[4:5], 10
	v_lshl_add_u64 v[6:7], v[100:101], 0, s[4:5]
	v_readlane_b32 s4, v108, 3
	s_ashr_i32 s5, s4, 31
	v_readlane_b32 s30, v108, 5
	s_lshl_b64 s[4:5], s[4:5], 10
	s_ashr_i32 s31, s30, 31
	global_load_dwordx4 v[88:91], v[4:5], off
	global_load_dwordx4 v[80:83], v[6:7], off
	v_lshl_add_u64 v[4:5], v[100:101], 0, s[4:5]
	s_lshl_b64 s[30:31], s[30:31], 10
	global_load_dwordx4 v[68:71], v[4:5], off
	v_lshl_add_u64 v[4:5], v[100:101], 0, s[30:31]
	v_readlane_b32 s30, v108, 6
	s_ashr_i32 s31, s30, 31
	s_lshl_b64 s[30:31], s[30:31], 10
	v_lshl_add_u64 v[6:7], v[100:101], 0, s[30:31]
	v_readlane_b32 s30, v108, 7
	v_readlane_b32 s4, v108, 4
	s_ashr_i32 s31, s30, 31
	s_lshl_b64 s[30:31], s[30:31], 10
	s_ashr_i32 s5, s4, 31
	v_lshl_add_u64 v[8:9], v[100:101], 0, s[30:31]
	s_lshl_b64 s[4:5], s[4:5], 10
	v_add_co_u32_e32 v0, vcc, 0x10000, v0
	global_load_dwordx4 v[40:43], v[8:9], off
	global_load_dwordx4 v[60:63], v[4:5], off
	global_load_dwordx4 v[48:51], v[6:7], off
	v_lshl_add_u64 v[4:5], v[100:101], 0, s[4:5]
	v_addc_co_u32_e32 v1, vcc, 0, v1, vcc
	global_load_dwordx4 v[76:79], v[4:5], off
	global_load_dwordx4 v[92:95], v[2:3], off
	global_load_dword v158, v[0:1], off
	v_bfi_b32 v1, s27, v113, v112
	v_mul_f32_e32 v0, 0.5, v111
	v_add_f32_e32 v1, 1.0, v1
	v_mul_f32_e32 v0, v0, v1
	v_mul_f32_e32 v0, v110, v0
	v_mul_f32_e32 v159, v114, v0
	v_mov_b32_e32 v118, 0
	s_mov_b32 s40, 0
	v_mov_b32_e32 v119, v118
	v_mov_b32_e32 v122, v118
	v_mov_b32_e32 v123, v118
	v_mov_b32_e32 v144, v118
	v_mov_b32_e32 v145, v118
	v_mov_b32_e32 v142, v118
	v_mov_b32_e32 v143, v118
	v_mov_b32_e32 v140, v118
	v_mov_b32_e32 v141, v118
	v_mov_b32_e32 v138, v118
	v_mov_b32_e32 v139, v118
	v_mov_b32_e32 v134, v118
	v_mov_b32_e32 v135, v118
	v_mov_b32_e32 v132, v118
	v_mov_b32_e32 v133, v118
	v_mov_b32_e32 v130, v118
	v_mov_b32_e32 v131, v118
	v_mov_b32_e32 v126, v118
	v_mov_b32_e32 v127, v118
	v_mov_b32_e32 v124, v118
	v_mov_b32_e32 v125, v118
	v_mov_b32_e32 v120, v118
	v_mov_b32_e32 v121, v118
	v_mov_b32_e32 v116, v118
	v_mov_b32_e32 v117, v118
	v_mov_b32_e32 v114, v118
	v_mov_b32_e32 v115, v118
	v_mov_b32_e32 v112, v118
	v_mov_b32_e32 v113, v118
	v_mov_b32_e32 v110, v118
	v_mov_b32_e32 v111, v118
	s_cmp_eq_u32 s84, 0x100
	s_cbranch_scc0 .Lp10_nobar2
	s_barrier
.Lp10_nobar2:
.LBB0_905:
	s_add_i32 s39, s40, 8
	v_readlane_b32 s4, v108, s39
	s_ashr_i32 s5, s4, 31
	s_lshl_b64 s[4:5], s[4:5], 10
	s_add_i32 s38, s40, 9
	v_lshl_add_u64 v[32:33], v[100:101], 0, s[4:5]
	v_readlane_b32 s4, v108, s38
	s_ashr_i32 s5, s4, 31
	s_lshl_b64 s[4:5], s[4:5], 10
	s_add_i32 s37, s40, 10
	v_lshl_add_u64 v[34:35], v[100:101], 0, s[4:5]
	v_readlane_b32 s4, v108, s37
	s_ashr_i32 s5, s4, 31
	s_lshl_b64 s[4:5], s[4:5], 10
	s_add_i32 s36, s40, 11
	global_load_dwordx4 v[84:87], v[32:33], off
	global_load_dwordx4 v[72:75], v[34:35], off
	v_lshl_add_u64 v[32:33], v[100:101], 0, s[4:5]
	v_readlane_b32 s4, v108, s36
	s_ashr_i32 s5, s4, 31
	s_lshl_b64 s[4:5], s[4:5], 10
	s_add_i32 s35, s40, 12
	v_lshl_add_u64 v[34:35], v[100:101], 0, s[4:5]
	v_readlane_b32 s4, v108, s35
	s_ashr_i32 s5, s4, 31
	s_lshl_b64 s[4:5], s[4:5], 10
	s_add_i32 s34, s40, 13
	global_load_dwordx4 v[64:67], v[32:33], off
	global_load_dwordx4 v[56:59], v[34:35], off
	v_lshl_add_u64 v[32:33], v[100:101], 0, s[4:5]
	v_readlane_b32 s4, v108, s34
	s_ashr_i32 s5, s4, 31
	s_lshl_b64 s[4:5], s[4:5], 10
	s_add_i32 s33, s40, 14
	v_lshl_add_u64 v[34:35], v[100:101], 0, s[4:5]
	v_readlane_b32 s4, v108, s33
	s_ashr_i32 s5, s4, 31
	s_lshl_b64 s[4:5], s[4:5], 10
	s_add_i32 s31, s40, 15
	global_load_dwordx4 v[52:55], v[32:33], off
	global_load_dwordx4 v[44:47], v[34:35], off
	v_lshl_add_u64 v[32:33], v[100:101], 0, s[4:5]
	v_readlane_b32 s4, v108, s31
	s_ashr_i32 s5, s4, 31
	s_lshl_b64 s[4:5], s[4:5], 10
	v_lshl_add_u64 v[34:35], v[100:101], 0, s[4:5]
	global_load_dwordx4 v[36:39], v[32:33], off
	s_nop 0
	global_load_dwordx4 v[32:35], v[34:35], off
	s_add_i32 s12, s40, 4
	s_add_i32 s30, s40, 6
	s_add_i32 s4, s40, 1
	s_add_i32 s5, s40, 2
	s_add_i32 s10, s40, 3
	s_add_i32 s14, s40, 5
	s_add_i32 s41, s40, 7
	v_readlane_b32 s16, v159, s12
	v_readlane_b32 s12, v159, s30
	s_add_i32 s30, s40, 16
	s_cmp_gt_u32 s40, 47
	v_readlane_b32 s24, v159, s40
	v_readlane_b32 s22, v159, s4
	v_readlane_b32 s20, v159, s5
	v_readlane_b32 s18, v159, s10
	v_readlane_b32 s14, v159, s14
	s_cselect_b64 s[4:5], -1, 0
	s_cmp_lt_u32 s40, 48
	v_readlane_b32 s10, v159, s41
	s_cbranch_scc0 .Lp10_dmy_907
	v_readlane_b32 s42, v108, s30
	s_ashr_i32 s43, s42, 31
	s_lshl_b64 s[42:43], s[42:43], 10
	s_add_i32 s41, s40, 17
	v_lshl_add_u64 v[0:1], v[100:101], 0, s[42:43]
	v_readlane_b32 s42, v108, s41
	s_ashr_i32 s43, s42, 31
	s_lshl_b64 s[42:43], s[42:43], 10
	s_add_i32 s41, s40, 18
	v_lshl_add_u64 v[2:3], v[100:101], 0, s[42:43]
	v_readlane_b32 s42, v108, s41
	s_ashr_i32 s43, s42, 31
	s_lshl_b64 s[42:43], s[42:43], 10
	s_add_i32 s41, s40, 19
	v_lshl_add_u64 v[8:9], v[100:101], 0, s[42:43]
	v_readlane_b32 s42, v108, s41
	s_ashr_i32 s43, s42, 31
	s_lshl_b64 s[42:43], s[42:43], 10
	s_add_i32 s41, s40, 20
	v_lshl_add_u64 v[10:11], v[100:101], 0, s[42:43]
	v_readlane_b32 s42, v108, s41
	s_ashr_i32 s43, s42, 31
	s_lshl_b64 s[42:43], s[42:43], 10
	s_add_i32 s41, s40, 21
	v_lshl_add_u64 v[16:17], v[100:101], 0, s[42:43]
	v_readlane_b32 s42, v108, s41
	s_ashr_i32 s43, s42, 31
	s_lshl_b64 s[42:43], s[42:43], 10
	s_add_i32 s41, s40, 22
	s_add_i32 s40, s40, 23
	v_lshl_add_u64 v[18:19], v[100:101], 0, s[42:43]
	v_readlane_b32 s42, v108, s41
	v_readlane_b32 s40, v108, s40
	s_ashr_i32 s43, s42, 31
	s_ashr_i32 s41, s40, 31
	s_lshl_b64 s[42:43], s[42:43], 10
	s_lshl_b64 s[40:41], s[40:41], 10
	v_lshl_add_u64 v[24:25], v[100:101], 0, s[42:43]
	v_lshl_add_u64 v[26:27], v[100:101], 0, s[40:41]
	global_load_dwordx4 v[4:7], v[0:1], off
	s_nop 0
	global_load_dwordx4 v[0:3], v[2:3], off
	s_nop 0
	global_load_dwordx4 v[12:15], v[8:9], off
	s_nop 0
	global_load_dwordx4 v[8:11], v[10:11], off
	s_nop 0
	global_load_dwordx4 v[20:23], v[16:17], off
	s_nop 0
	global_load_dwordx4 v[16:19], v[18:19], off
	s_nop 0
	global_load_dwordx4 v[28:31], v[24:25], off
	s_nop 0
	global_load_dwordx4 v[24:27], v[26:27], off
	s_branch .LBB0_907
